# attention bias LDS reads de-serialized; phase-H prenorm: j=1..3 param loads hoisted above the wave reduction with counted vmcnt
# speedup vs baseline: 1.0288x; 1.0112x over previous
; #define LAS __attribute__((address_space(3)))
; __device__ __forceinline__ void attn_all(KArgs& a, LAS unsigned char* lds, int l) {
;     ...
;             if (t < n_local) {
;                 const int krow = krow_lo + t; const float radd = (unsigned)(krow - r0q) < 8u ? 0.f : -1e30f;
;                 const LAS float* bp = bp0 + krow * 31;
;                 float bv[16];
; #pragma unroll
;                 for (int j = 0; j < 16; ++j) bv[j] = bp[8 * (j >> 2) + (j & 3)];
; #pragma unroll
;                 for (int j = 0; j < 16; ++j) sv[j] = fmaf(S[j], 0.125f * 1.44269504f, bv[j] + (cadd[j] + radd));
.LBB0_516:
	s_andn2_b64 vcc, exec, s[0:1]
	s_cbranch_vccnz .LBB0_518
	ds_read2_b32 v[162:163], v109 offset1:1
	ds_read2_b32 v[164:165], v109 offset0:2 offset1:3
	ds_read2_b32 v[166:167], v109 offset0:8 offset1:9
	ds_read2_b32 v[168:169], v109 offset0:10 offset1:11
	ds_read2_b32 v[170:171], v109 offset0:16 offset1:17
	ds_read2_b32 v[172:173], v109 offset0:18 offset1:19
	ds_read2_b32 v[174:175], v109 offset0:24 offset1:25
	ds_read2_b32 v[176:177], v109 offset0:26 offset1:27
	v_add_u32_e32 v0, s23, v159
	v_cmp_gt_u32_e32 vcc, 8, v0
	s_nop 1
	v_cndmask_b32_e64 v0, v228, 0, vcc
	v_pk_add_f32 v[178:179], v[112:113], v[0:1] op_sel_hi:[1,0]
	v_pk_add_f32 v[180:181], v[114:115], v[0:1] op_sel_hi:[1,0]
	v_pk_add_f32 v[182:183], v[116:117], v[0:1] op_sel_hi:[1,0]
	v_pk_add_f32 v[184:185], v[118:119], v[0:1] op_sel_hi:[1,0]
	v_pk_add_f32 v[186:187], v[120:121], v[0:1] op_sel_hi:[1,0]
	v_pk_add_f32 v[188:189], v[122:123], v[0:1] op_sel_hi:[1,0]
	v_pk_add_f32 v[190:191], v[124:125], v[0:1] op_sel_hi:[1,0]
	v_pk_add_f32 v[192:193], v[126:127], v[0:1] op_sel_hi:[1,0]
	s_waitcnt lgkmcnt(7)
	v_pk_add_f32 v[178:179], v[178:179], v[162:163]
	s_waitcnt lgkmcnt(6)
	v_pk_add_f32 v[180:181], v[180:181], v[164:165]
	v_pk_fma_f32 v[14:15], v[48:49], s[30:31], v[178:179] op_sel_hi:[1,0,1]
	s_waitcnt lgkmcnt(5)
	v_pk_add_f32 v[182:183], v[182:183], v[166:167]
	v_pk_fma_f32 v[134:135], v[50:51], s[30:31], v[180:181] op_sel_hi:[1,0,1]
	s_waitcnt lgkmcnt(4)
	v_pk_add_f32 v[184:185], v[184:185], v[168:169]
	v_pk_fma_f32 v[136:137], v[52:53], s[30:31], v[182:183] op_sel_hi:[1,0,1]
	s_waitcnt lgkmcnt(3)
	v_pk_add_f32 v[186:187], v[186:187], v[170:171]
	v_pk_fma_f32 v[138:139], v[54:55], s[30:31], v[184:185] op_sel_hi:[1,0,1]
	s_waitcnt lgkmcnt(2)
	v_pk_add_f32 v[188:189], v[188:189], v[172:173]
	v_pk_fma_f32 v[140:141], v[56:57], s[30:31], v[186:187] op_sel_hi:[1,0,1]
	s_waitcnt lgkmcnt(1)
	v_pk_add_f32 v[190:191], v[190:191], v[174:175]
	v_pk_fma_f32 v[142:143], v[58:59], s[30:31], v[188:189] op_sel_hi:[1,0,1]
	s_waitcnt lgkmcnt(0)
	v_pk_add_f32 v[192:193], v[192:193], v[176:177]
	v_pk_fma_f32 v[144:145], v[60:61], s[30:31], v[190:191] op_sel_hi:[1,0,1]
	s_nop 0
	v_pk_fma_f32 v[146:147], v[62:63], s[30:31], v[192:193] op_sel_hi:[1,0,1]

; __device__ __forceinline__ unsigned pk2(float lo, float hi) { const f32x2 v = {lo, hi}; return __builtin_bit_cast(unsigned, __builtin_convertvector(v, bf16v2_t)); }
; __device__ __forceinline__ void prenorm_row(float* xr, const float* g, const float* shift, const float* scale, bf16_t* orow, int lane, const LAS unsigned char* tmap, const float* PB, int r) {
;     ...
; #pragma unroll
;     for (int j = 0; j < 4; ++j) s += (v[j].x * v[j].x + v[j].y * v[j].y) + (v[j].z * v[j].z + v[j].w * v[j].w);
;     const float rstd = rsqrtf(wave_sum(s) * (1.f / DM) + 1e-6f);
; #pragma unroll
;     for (int j = 0; j < 4; ++j) {
;         const f32x4 gg = ((const f32x4*)g)[lane + 64 * j], sh = ((const f32x4*)shift)[lane + 64 * j], sc = ((const f32x4*)scale)[lane + 64 * j];
;         const f32x4 y = v[j] * rstd * gg * (sc + 1.f) + sh;
;         u32x2 o; o.x = pk2(y.x, y.y); o.y = pk2(y.z, y.w);
;         ((u32x2*)orow)[lane + 64 * j] = o;
;     }
.LBB0_1131:
	s_waitcnt vmcnt(0)
	v_pk_mul_f32 v[26:27], v[4:5], v[4:5]
	v_pk_mul_f32 v[28:29], v[2:3], v[2:3]
	v_pk_mul_f32 v[20:21], v[8:9], v[8:9]
	v_pk_mul_f32 v[24:25], v[6:7], v[6:7]
	v_pk_mov_b32 v[30:31], v[28:29], v[26:27] op_sel:[1,0]
	v_mov_b32_e32 v29, v27
	v_pk_add_f32 v[26:27], v[30:31], v[28:29]
	v_pk_mov_b32 v[28:29], v[24:25], v[20:21] op_sel:[1,0]
	v_mov_b32_e32 v25, v21
	v_pk_add_f32 v[20:21], v[28:29], v[24:25]
	v_cndmask_b32_e64 v18, v66, 8, s[40:41]
	v_pk_add_f32 v[20:21], v[20:21], v[20:21] op_sel_hi:[0,1]
	v_mul_f32_e32 v20, v10, v10
	v_mul_hi_i32_i24_e32 v19, 0x6000, v18
	v_mul_i32_i24_e32 v18, 0x6000, v18
	v_pk_fma_f32 v[24:25], v[10:11], v[10:11], v[20:21] op_sel_hi:[1,1,0]
	v_mul_f32_e32 v20, v12, v12
	v_lshl_add_u64 v[22:23], s[22:23], 0, v[18:19]
	s_mov_b64 s[0:1], 0x1000
	v_pk_add_f32 v[26:27], v[26:27], v[26:27] op_sel_hi:[0,1]
	v_pk_fma_f32 v[28:29], v[12:13], v[12:13], v[20:21] op_sel_hi:[1,1,0]
	v_lshl_add_u64 v[18:19], v[22:23], 0, s[0:1]
	v_mul_f32_e32 v24, v46, v46
	v_mul_f32_e32 v28, v47, v47
	v_mul_f32_e32 v26, v48, v48
	v_mul_f32_e32 v20, v49, v49
	v_pk_add_f32 v[24:25], v[24:25], v[28:29]
	v_pk_add_f32 v[20:21], v[26:27], v[20:21]
	v_lshl_add_u64 v[22:23], v[22:23], 0, v[0:1]
	v_lshl_add_u64 v[32:33], v[18:19], 0, v[0:1]
	v_pk_add_f32 v[20:21], v[24:25], v[20:21]
	global_load_dwordx4 v[24:27], v[56:57], off
	global_load_dwordx4 v[28:31], v[22:23], off
	v_add_f32_e32 v20, v20, v21
	global_load_dwordx4 v[32:35], v[32:33], off
	ds_bpermute_b32 v21, v53, v20
	s_mov_b32 s0, 0x800000
	v_mov_b32_e32 v61, v1
	v_mov_b32_e32 v63, v1
	v_mov_b32_e32 v65, v1
	v_lshl_add_u64 v[184:185], v[18:19], 0, v[60:61]
	v_lshl_add_u64 v[186:187], v[18:19], 0, v[62:63]
	v_lshl_add_u64 v[188:189], v[18:19], 0, v[64:65]
	global_load_dwordx4 v[148:151], v[56:57], off offset:1024
	global_load_dwordx4 v[152:155], v[22:23], off offset:1024
	global_load_dwordx4 v[156:159], v[184:185], off
	global_load_dwordx4 v[160:163], v[56:57], off offset:2048
	global_load_dwordx4 v[164:167], v[22:23], off offset:2048
	global_load_dwordx4 v[168:171], v[186:187], off
	global_load_dwordx4 v[172:175], v[56:57], off offset:3072
	global_load_dwordx4 v[176:179], v[22:23], off offset:3072
	global_load_dwordx4 v[180:183], v[188:189], off
	s_waitcnt lgkmcnt(0)
	v_add_f32_e32 v20, v20, v21
	ds_bpermute_b32 v21, v70, v20
	v_add_u32_e32 v50, s16, v50
	v_add_u32_e32 v75, s2, v75
	s_waitcnt lgkmcnt(0)
	v_add_f32_e32 v20, v20, v21
	ds_bpermute_b32 v21, v71, v20
	s_waitcnt lgkmcnt(0)
	v_add_f32_e32 v20, v20, v21
	ds_bpermute_b32 v21, v72, v20
	s_waitcnt lgkmcnt(0)
	v_add_f32_e32 v20, v20, v21
	ds_bpermute_b32 v21, v73, v20
	s_waitcnt lgkmcnt(0)
	v_add_f32_e32 v20, v20, v21
	ds_bpermute_b32 v21, v74, v20
	s_waitcnt lgkmcnt(0)
	v_add_f32_e32 v20, v20, v21
	v_fmamk_f32 v20, v20, 0x3a800000, v219
	v_cmp_gt_f32_e32 vcc, s0, v20
	v_mul_f32_e32 v21, 0x4b800000, v20
	s_mov_b32 s0, 0x33f8000
	v_cndmask_b32_e32 v20, v20, v21, vcc
	v_rsq_f32_e32 v20, v20
	s_nop 0
	v_mul_f32_e32 v21, 0x45800000, v20
	v_cndmask_b32_e32 v20, v20, v21, vcc
	v_pk_mul_f32 v[4:5], v[4:5], v[20:21] op_sel_hi:[1,0]
	v_pk_mul_f32 v[2:3], v[2:3], v[20:21] op_sel_hi:[1,0]
	v_pk_mul_f32 v[6:7], v[6:7], v[20:21] op_sel_hi:[1,0]
	v_pk_mul_f32 v[10:11], v[10:11], v[20:21] op_sel_hi:[1,0]
	v_pk_mul_f32 v[14:15], v[14:15], v[20:21] op_sel_hi:[1,0]
	s_waitcnt vmcnt(11)
	v_pk_mul_f32 v[2:3], v[24:25], v[2:3]
	v_pk_mul_f32 v[4:5], v[26:27], v[4:5]
	s_waitcnt vmcnt(9)
	v_pk_add_f32 v[26:27], v[32:33], 1.0 op_sel_hi:[1,0]
	v_pk_add_f32 v[24:25], v[34:35], 1.0 op_sel_hi:[1,0]
	v_pk_fma_f32 v[2:3], v[26:27], v[2:3], v[28:29]
	v_pk_fma_f32 v[4:5], v[24:25], v[4:5], v[30:31]
	v_cvt_pk_bf16_f32 v24, v2, v3
	v_lshl_add_u64 v[2:3], s[54:55], 0, v[58:59]
	v_add_co_u32_e32 v2, vcc, s0, v2
	v_cvt_pk_bf16_f32 v25, v4, v5
	s_nop 0
	v_addc_co_u32_e32 v3, vcc, 0, v3, vcc
	global_store_dwordx2 v[2:3], v[24:25], off
	v_pk_mul_f32 v[4:5], v[8:9], v[20:21] op_sel_hi:[1,0]
	s_mov_b32 s0, 0x87ff
	v_cmp_lt_i32_e32 vcc, s0, v50
	v_lshl_add_u64 v[58:59], v[58:59], 0, s[36:37]
	s_or_b64 s[38:39], vcc, s[38:39]
	s_waitcnt vmcnt(9)
	v_pk_mul_f32 v[6:7], v[148:149], v[6:7]
	v_pk_mul_f32 v[4:5], v[150:151], v[4:5]
	s_waitcnt vmcnt(7)
	v_pk_add_f32 v[8:9], v[158:159], 1.0 op_sel_hi:[1,0]
	v_pk_add_f32 v[24:25], v[156:157], 1.0 op_sel_hi:[1,0]
	v_pk_fma_f32 v[4:5], v[8:9], v[4:5], v[154:155]
	v_pk_fma_f32 v[6:7], v[24:25], v[6:7], v[152:153]
	s_nop 0
	v_cvt_pk_bf16_f32 v6, v6, v7
	v_cvt_pk_bf16_f32 v7, v4, v5
	global_store_dwordx2 v[2:3], v[6:7], off offset:512
	v_pk_mul_f32 v[8:9], v[12:13], v[20:21] op_sel_hi:[1,0]
	s_waitcnt vmcnt(7)
	v_pk_mul_f32 v[4:5], v[160:161], v[10:11]
	v_pk_mul_f32 v[6:7], v[162:163], v[8:9]
	s_waitcnt vmcnt(5)
	v_pk_add_f32 v[8:9], v[170:171], 1.0 op_sel_hi:[1,0]
	v_pk_add_f32 v[10:11], v[168:169], 1.0 op_sel_hi:[1,0]
	v_pk_fma_f32 v[6:7], v[8:9], v[6:7], v[166:167]
	v_pk_fma_f32 v[4:5], v[10:11], v[4:5], v[164:165]
	s_nop 0
	v_cvt_pk_bf16_f32 v4, v4, v5
	v_cvt_pk_bf16_f32 v5, v6, v7
	global_store_dwordx2 v[2:3], v[4:5], off offset:1024
	s_waitcnt vmcnt(5)
	v_pk_mul_f32 v[4:5], v[172:173], v[14:15]
	v_pk_mul_f32 v[12:13], v[16:17], v[20:21] op_sel_hi:[1,0]
	s_waitcnt vmcnt(3)
	v_pk_add_f32 v[14:15], v[180:181], 1.0 op_sel_hi:[1,0]
	v_pk_mul_f32 v[6:7], v[174:175], v[12:13]
	v_pk_add_f32 v[12:13], v[182:183], 1.0 op_sel_hi:[1,0]
	v_pk_fma_f32 v[4:5], v[14:15], v[4:5], v[176:177]
	v_pk_fma_f32 v[6:7], v[12:13], v[6:7], v[178:179]
	v_cvt_pk_bf16_f32 v4, v4, v5
	v_cvt_pk_bf16_f32 v5, v6, v7
	global_store_dwordx2 v[2:3], v[4:5], off offset:1536
	s_andn2_b64 exec, exec, s[38:39]
	s_cbranch_execz .LBB0_1145
